# v33: per-half A/B of the static priority raise: s_setprio 1 on waves 0-3 (first key half) over the prompt-attention units instead of waves 4-7
# speedup vs baseline: 1.0127x; 1.0127x over previous
.LBB0_1314:
	s_cmp_eq_u32 s62, 0
	s_cbranch_scc0 .Lattn_prio_done
	s_setprio 1
